# gate/up GEMM K-loop: LDS-DMA loads use SGPR base + 32-bit VGPR offset (no per-load 64-bit VALU address adds in the loader wave)
# speedup vs baseline: 1.0113x; 1.0113x over previous
; #define PG8_STAGE(bufoff, gbase, voff) do { _Pragma("unroll") for (int _i = 0; _i < 2; ++_i) \
;         __builtin_amdgcn_global_load_lds((const unsigned*)((const char*)(gbase) + (voff)[_i]), (PG8_LAS unsigned*)(lds + (bufoff) + ldsw + _i * 8192), 16, 0, 0); } while (0)
; #define PG8_LDA(dst, b, h) do { _Pragma("unroll") for (int m = 0; m < 4; ++m) _Pragma("unroll") for (int k = 0; k < 2; ++k) dst[m][k] = *(const PG8_LAS bf16x8*)(lds + PG8_SA(b, h) + aoff + m * 2048 + k * 1024); } while (0)
; #define PG8_LDB(dst, b, h) do { _Pragma("unroll") for (int n = 0; n < 2; ++n) _Pragma("unroll") for (int k = 0; k < 2; ++k) dst[n][k] = *(const PG8_LAS bf16x8*)(lds + PG8_SB(b, h) + boff + n * 2048 + k * 1024); } while (0)
; #define PG8_MMA(ai, bj, At, Bt) do { __builtin_amdgcn_s_setprio(1); _Pragma("unroll") for (int m = 0; m < 4; ++m) _Pragma("unroll") for (int n = 0; n < 2; ++n) _Pragma("unroll") for (int k = 0; k < 2; ++k) \
;         acc[ai][bj][m][n] = __builtin_amdgcn_mfma_f32_16x16x32_bf16(Bt[n][k], At[m][k], acc[ai][bj][m][n], 0, 0, 0); __builtin_amdgcn_s_setprio(0); } while (0)
; #define PG8_WAIT_V(n) asm volatile("s_waitcnt vmcnt(" #n ")" ::: "memory")
; #define PG8_WAIT_L(n) asm volatile("s_waitcnt lgkmcnt(" #n ")" ::: "memory")
; template <class Epi, class Sched, bool ALIGN_EPI = false, bool SP2 = false>
; __device__ __forceinline__ void gemm_phase(PG8_LAS unsigned char* lds, const Gemm g, const Sched& S, const Epi& E) {
;     ...
;             const bool last = (t == nt - 2);
;             const char* a1 = cA + (size_t)(t + 1) * kstep;
;             const char* a2 = last ? nA : cA + (size_t)(t + 2) * kstep; const char* b2 = last ? nB : cB + (size_t)(t + 2) * kstep;
;             const char* a3 = a2 + kstep; const char* b3 = b2 + kstep;
;             if (last && has_next) S.a_ready(nxt);
;             if constexpr (SP2) {
;             PG8_LDB(B0, 0, 0); PG8_LDB(B1, 0, 1); PG8_SCHED; PG8_LDA(At, 0, 0); PG8_STAGE(PG8_SA(1, 1), a1 + hstep, voffA);
;             PG8_WAIT_V(8); PG8_WAIT_L(0); PG8_BAR; PG8_MMA(0, 0, At, B0); PG8_MMA(0, 1, At, B1); PG8_BAR; PG8_SCHED;
;             PG8_LDA(At, 0, 1); PG8_STAGE(PG8_SB(0, 0), b2, voffB); PG8_STAGE(PG8_SB(0, 1), b2 + hstep, voffB); PG8_STAGE(PG8_SA(0, 0), a2, voffA);
;             PG8_WAIT_V(8); PG8_WAIT_L(0); PG8_BAR; PG8_MMA(1, 0, At, B0); PG8_MMA(1, 1, At, B1); PG8_BAR; PG8_SCHED;
.LBB0_431:
	s_add_u32 s54, s42, s52
	s_addc_u32 s55, s43, s53
	s_add_u32 s54, s54, 0x100
	s_addc_u32 s55, s55, 0
	s_add_u32 s75, s29, s52
	s_addc_u32 s76, s33, s53
	s_cmpk_eq_i32 s52, 0xf00
	s_cselect_b32 s57, s25, s55
	s_cselect_b32 s56, s47, s54
	s_cselect_b32 s55, s45, s76
	s_cselect_b32 s54, s73, s75
	s_add_i32 s75, 0, 0x10000
	v_add_u32_e32 v152, s75, v145
	s_add_i32 s78, 0, 0x14000
	ds_read_b128 v[148:151], v152
	ds_read_b128 v[170:173], v152 offset:1024
	ds_read_b128 v[174:177], v152 offset:2048
	ds_read_b128 v[178:181], v152 offset:3072
	v_add_u32_e32 v152, s78, v145
	ds_read_b128 v[182:185], v152
	ds_read_b128 v[186:189], v152 offset:1024
	ds_read_b128 v[190:193], v152 offset:2048
	ds_read_b128 v[194:197], v152 offset:3072
	s_add_u32 s76, s42, s52
	s_addc_u32 s77, s43, s53
	s_add_u32 s76, s76, 0x80080
	s_addc_u32 s77, s77, 0
	s_add_i32 m0, s15, 0xc000
	ds_read_b128 v[198:201], v147
	ds_read_b128 v[202:205], v147 offset:1024
	ds_read_b128 v[206:209], v147 offset:2048
	ds_read_b128 v[210:213], v147 offset:3072
	ds_read_b128 v[220:223], v147 offset:4096
	ds_read_b128 v[224:227], v147 offset:5120
	ds_read_b128 v[228:231], v147 offset:6144
	ds_read_b128 v[232:235], v147 offset:7168
	global_load_lds_dwordx4 v136, s[76:77]
	s_add_i32 m0, s15, 0xe000
	s_nop 0
	global_load_lds_dwordx4 v138, s[76:77]
	s_waitcnt vmcnt(8)
	s_waitcnt lgkmcnt(0)
	s_barrier
	s_setprio 1
	s_waitcnt lgkmcnt(0)
	v_mfma_f32_16x16x32_bf16 v[124:127], v[148:151], v[198:201], v[124:127]
	v_mfma_f32_16x16x32_bf16 v[120:123], v[174:177], v[198:201], v[120:123]
	v_mfma_f32_16x16x32_bf16 v[116:119], v[148:151], v[206:209], v[116:119]
	v_mfma_f32_16x16x32_bf16 v[112:115], v[174:177], v[206:209], v[112:115]
	v_mfma_f32_16x16x32_bf16 v[108:111], v[148:151], v[220:223], v[108:111]
	v_mfma_f32_16x16x32_bf16 v[104:107], v[174:177], v[220:223], v[104:107]
	v_mfma_f32_16x16x32_bf16 v[100:103], v[148:151], v[228:231], v[100:103]
	v_mfma_f32_16x16x32_bf16 v[96:99], v[174:177], v[228:231], v[96:99]
	v_mfma_f32_16x16x32_bf16 v[124:127], v[170:173], v[202:205], v[124:127]
	v_mfma_f32_16x16x32_bf16 v[120:123], v[178:181], v[202:205], v[120:123]
	v_mfma_f32_16x16x32_bf16 v[116:119], v[170:173], v[210:213], v[116:119]
	v_mfma_f32_16x16x32_bf16 v[112:115], v[178:181], v[210:213], v[112:115]
	v_mfma_f32_16x16x32_bf16 v[108:111], v[170:173], v[224:227], v[108:111]
	v_mfma_f32_16x16x32_bf16 v[104:107], v[178:181], v[224:227], v[104:107]
	v_mfma_f32_16x16x32_bf16 v[100:103], v[170:173], v[232:235], v[100:103]
	v_mfma_f32_16x16x32_bf16 v[96:99], v[178:181], v[232:235], v[96:99]
	s_setprio 0
	s_setprio 1
	v_mfma_f32_16x16x32_bf16 v[92:95], v[182:185], v[198:201], v[92:95]
	v_mfma_f32_16x16x32_bf16 v[88:91], v[190:193], v[198:201], v[88:91]
	v_mfma_f32_16x16x32_bf16 v[84:87], v[182:185], v[206:209], v[84:87]
	v_mfma_f32_16x16x32_bf16 v[80:83], v[190:193], v[206:209], v[80:83]
	v_mfma_f32_16x16x32_bf16 v[76:79], v[182:185], v[220:223], v[76:79]
	v_mfma_f32_16x16x32_bf16 v[72:75], v[190:193], v[220:223], v[72:75]
	v_mfma_f32_16x16x32_bf16 v[68:71], v[182:185], v[228:231], v[68:71]
	v_mfma_f32_16x16x32_bf16 v[64:67], v[190:193], v[228:231], v[64:67]
	v_mfma_f32_16x16x32_bf16 v[92:95], v[186:189], v[202:205], v[92:95]
	v_mfma_f32_16x16x32_bf16 v[88:91], v[194:197], v[202:205], v[88:91]
	v_mfma_f32_16x16x32_bf16 v[84:87], v[186:189], v[210:213], v[84:87]
	v_mfma_f32_16x16x32_bf16 v[80:83], v[194:197], v[210:213], v[80:83]
	v_mfma_f32_16x16x32_bf16 v[76:79], v[186:189], v[224:227], v[76:79]
	v_mfma_f32_16x16x32_bf16 v[72:75], v[194:197], v[224:227], v[72:75]
	v_mfma_f32_16x16x32_bf16 v[68:71], v[186:189], v[232:235], v[68:71]
	v_mfma_f32_16x16x32_bf16 v[64:67], v[194:197], v[232:235], v[64:67]
	s_setprio 0
	s_barrier
	s_add_i32 s75, s75, s65
	s_mov_b32 m0, s75
	ds_read_b128 v[198:201], v147 offset:16384
	ds_read_b128 v[202:205], v147 offset:17408
	ds_read_b128 v[206:209], v147 offset:18432
	ds_read_b128 v[210:213], v147 offset:19456
	ds_read_b128 v[220:223], v147 offset:20480
	ds_read_b128 v[224:227], v147 offset:21504
	ds_read_b128 v[228:231], v147 offset:22528
	ds_read_b128 v[232:235], v147 offset:23552
	global_load_lds_dwordx4 v130, s[54:55]
	s_add_i32 m0, s75, 0x2000
	s_add_u32 s76, s54, 0x80000
	s_addc_u32 s77, s55, 0
	s_add_i32 s75, s78, s65
	global_load_lds_dwordx4 v134, s[54:55]
	s_mov_b32 m0, s75
	s_nop 0
	global_load_lds_dwordx4 v130, s[76:77]
	s_add_i32 m0, s75, 0x2000
	s_nop 0
	global_load_lds_dwordx4 v134, s[76:77]
	s_mov_b32 m0, s15
	s_nop 0
	global_load_lds_dwordx4 v128, s[56:57]
	s_mov_b32 m0, s17
	s_nop 0
	global_load_lds_dwordx4 v132, s[56:57]
	s_waitcnt vmcnt(8)
	s_waitcnt lgkmcnt(0)
	s_barrier
; #define PG8_STAGE(bufoff, gbase, voff) do { _Pragma("unroll") for (int _i = 0; _i < 2; ++_i) \
;         __builtin_amdgcn_global_load_lds((const unsigned*)((const char*)(gbase) + (voff)[_i]), (PG8_LAS unsigned*)(lds + (bufoff) + ldsw + _i * 8192), 16, 0, 0); } while (0)
; #define PG8_LDA(dst, b, h) do { _Pragma("unroll") for (int m = 0; m < 4; ++m) _Pragma("unroll") for (int k = 0; k < 2; ++k) dst[m][k] = *(const PG8_LAS bf16x8*)(lds + PG8_SA(b, h) + aoff + m * 2048 + k * 1024); } while (0)
; #define PG8_LDB(dst, b, h) do { _Pragma("unroll") for (int n = 0; n < 2; ++n) _Pragma("unroll") for (int k = 0; k < 2; ++k) dst[n][k] = *(const PG8_LAS bf16x8*)(lds + PG8_SB(b, h) + boff + n * 2048 + k * 1024); } while (0)
; #define PG8_MMA(ai, bj, At, Bt) do { __builtin_amdgcn_s_setprio(1); _Pragma("unroll") for (int m = 0; m < 4; ++m) _Pragma("unroll") for (int n = 0; n < 2; ++n) _Pragma("unroll") for (int k = 0; k < 2; ++k) \
;         acc[ai][bj][m][n] = __builtin_amdgcn_mfma_f32_16x16x32_bf16(Bt[n][k], At[m][k], acc[ai][bj][m][n], 0, 0, 0); __builtin_amdgcn_s_setprio(0); } while (0)
; #define PG8_WAIT_V(n) asm volatile("s_waitcnt vmcnt(" #n ")" ::: "memory")
; #define PG8_WAIT_L(n) asm volatile("s_waitcnt lgkmcnt(" #n ")" ::: "memory")
; #define PG8_BAR __builtin_amdgcn_s_barrier()
; #define PG8_SCHED __builtin_amdgcn_sched_barrier(0)
; template <class Epi, class Sched, bool ALIGN_EPI = false, bool SP2 = false>
; __device__ __forceinline__ void gemm_phase(PG8_LAS unsigned char* lds, const Gemm g, const Sched& S, const Epi& E) {
;     ...
;             PG8_WAIT_V(8); PG8_WAIT_L(0); PG8_BAR; PG8_MMA(1, 0, At, B0); PG8_MMA(1, 1, At, B1); PG8_BAR; PG8_SCHED;
;             PG8_LDB(B0, 1, 0); PG8_LDB(B1, 1, 1); PG8_SCHED; PG8_LDA(At, 1, 0); PG8_STAGE(PG8_SA(0, 1), a2 + hstep, voffA);
;             PG8_WAIT_V(8); PG8_WAIT_L(0); PG8_BAR; PG8_MMA(0, 0, At, B0); PG8_MMA(0, 1, At, B1); PG8_BAR; PG8_SCHED;
	s_setprio 1
	s_waitcnt lgkmcnt(0)
	v_mfma_f32_16x16x32_bf16 v[60:63], v[148:151], v[198:201], v[60:63]
	v_mfma_f32_16x16x32_bf16 v[56:59], v[174:177], v[198:201], v[56:59]
	v_mfma_f32_16x16x32_bf16 v[52:55], v[148:151], v[206:209], v[52:55]
	v_mfma_f32_16x16x32_bf16 v[48:51], v[174:177], v[206:209], v[48:51]
	v_mfma_f32_16x16x32_bf16 v[44:47], v[148:151], v[220:223], v[44:47]
	v_mfma_f32_16x16x32_bf16 v[40:43], v[174:177], v[220:223], v[40:43]
	v_mfma_f32_16x16x32_bf16 v[36:39], v[148:151], v[228:231], v[36:39]
	v_mfma_f32_16x16x32_bf16 v[32:35], v[174:177], v[228:231], v[32:35]
	v_mfma_f32_16x16x32_bf16 v[60:63], v[170:173], v[202:205], v[60:63]
	v_mfma_f32_16x16x32_bf16 v[56:59], v[178:181], v[202:205], v[56:59]
	v_mfma_f32_16x16x32_bf16 v[52:55], v[170:173], v[210:213], v[52:55]
	v_mfma_f32_16x16x32_bf16 v[48:51], v[178:181], v[210:213], v[48:51]
	v_mfma_f32_16x16x32_bf16 v[44:47], v[170:173], v[224:227], v[44:47]
	v_mfma_f32_16x16x32_bf16 v[40:43], v[178:181], v[224:227], v[40:43]
	v_mfma_f32_16x16x32_bf16 v[36:39], v[170:173], v[232:235], v[36:39]
	v_mfma_f32_16x16x32_bf16 v[32:35], v[178:181], v[232:235], v[32:35]
	s_setprio 0
	s_setprio 1
	v_mfma_f32_16x16x32_bf16 v[28:31], v[182:185], v[198:201], v[28:31]
	v_mfma_f32_16x16x32_bf16 v[24:27], v[190:193], v[198:201], v[24:27]
	v_mfma_f32_16x16x32_bf16 v[20:23], v[182:185], v[206:209], v[20:23]
	v_mfma_f32_16x16x32_bf16 v[16:19], v[190:193], v[206:209], v[16:19]
	v_mfma_f32_16x16x32_bf16 v[12:15], v[182:185], v[220:223], v[12:15]
	v_mfma_f32_16x16x32_bf16 v[8:11], v[190:193], v[220:223], v[8:11]
	v_mfma_f32_16x16x32_bf16 v[4:7], v[182:185], v[228:231], v[4:7]
	v_mfma_f32_16x16x32_bf16 v[0:3], v[190:193], v[228:231], v[0:3]
	v_mfma_f32_16x16x32_bf16 v[28:31], v[186:189], v[202:205], v[28:31]
	v_mfma_f32_16x16x32_bf16 v[24:27], v[194:197], v[202:205], v[24:27]
	v_mfma_f32_16x16x32_bf16 v[20:23], v[186:189], v[210:213], v[20:23]
	v_mfma_f32_16x16x32_bf16 v[16:19], v[194:197], v[210:213], v[16:19]
	v_mfma_f32_16x16x32_bf16 v[12:15], v[186:189], v[224:227], v[12:15]
	v_mfma_f32_16x16x32_bf16 v[8:11], v[194:197], v[224:227], v[8:11]
	v_mfma_f32_16x16x32_bf16 v[4:7], v[186:189], v[232:235], v[4:7]
	v_mfma_f32_16x16x32_bf16 v[0:3], v[194:197], v[232:235], v[0:3]
	s_setprio 0
	s_barrier
	s_add_i32 s75, 0, 0x18000
	v_add_u32_e32 v152, s75, v145
	s_add_i32 s76, 0, 0x1c000
	ds_read_b128 v[148:151], v152
	ds_read_b128 v[170:173], v152 offset:1024
	ds_read_b128 v[174:177], v152 offset:2048
	ds_read_b128 v[178:181], v152 offset:3072
	v_add_u32_e32 v152, s76, v145
	ds_read_b128 v[182:185], v152
	ds_read_b128 v[186:189], v152 offset:1024
	ds_read_b128 v[190:193], v152 offset:2048
	ds_read_b128 v[194:197], v152 offset:3072
	s_add_u32 s56, s56, 0x80000
	s_addc_u32 s57, s57, 0
	s_mov_b32 m0, s68
	ds_read_b128 v[198:201], v147 offset:32768
	ds_read_b128 v[202:205], v147 offset:33792
	ds_read_b128 v[206:209], v147 offset:34816
	ds_read_b128 v[210:213], v147 offset:35840
	ds_read_b128 v[220:223], v147 offset:36864
	ds_read_b128 v[224:227], v147 offset:37888
	ds_read_b128 v[228:231], v147 offset:38912
	ds_read_b128 v[232:235], v147 offset:39936
	global_load_lds_dwordx4 v128, s[56:57]
	s_mov_b32 m0, s69
	s_nop 0
	global_load_lds_dwordx4 v132, s[56:57]
	s_waitcnt vmcnt(8)
	s_waitcnt lgkmcnt(0)
	s_barrier
	s_setprio 1
	s_waitcnt lgkmcnt(0)
	v_mfma_f32_16x16x32_bf16 v[124:127], v[148:151], v[198:201], v[124:127]
	v_mfma_f32_16x16x32_bf16 v[120:123], v[174:177], v[198:201], v[120:123]
	v_mfma_f32_16x16x32_bf16 v[116:119], v[148:151], v[206:209], v[116:119]
	v_mfma_f32_16x16x32_bf16 v[112:115], v[174:177], v[206:209], v[112:115]
	v_mfma_f32_16x16x32_bf16 v[108:111], v[148:151], v[220:223], v[108:111]
	v_mfma_f32_16x16x32_bf16 v[104:107], v[174:177], v[220:223], v[104:107]
	v_mfma_f32_16x16x32_bf16 v[100:103], v[148:151], v[228:231], v[100:103]
	v_mfma_f32_16x16x32_bf16 v[96:99], v[174:177], v[228:231], v[96:99]
	v_mfma_f32_16x16x32_bf16 v[124:127], v[170:173], v[202:205], v[124:127]
	v_mfma_f32_16x16x32_bf16 v[120:123], v[178:181], v[202:205], v[120:123]
	v_mfma_f32_16x16x32_bf16 v[116:119], v[170:173], v[210:213], v[116:119]
	v_mfma_f32_16x16x32_bf16 v[112:115], v[178:181], v[210:213], v[112:115]
	v_mfma_f32_16x16x32_bf16 v[108:111], v[170:173], v[224:227], v[108:111]
	v_mfma_f32_16x16x32_bf16 v[104:107], v[178:181], v[224:227], v[104:107]
	v_mfma_f32_16x16x32_bf16 v[100:103], v[170:173], v[232:235], v[100:103]
	v_mfma_f32_16x16x32_bf16 v[96:99], v[178:181], v[232:235], v[96:99]
	s_setprio 0
	s_setprio 1
	v_mfma_f32_16x16x32_bf16 v[92:95], v[182:185], v[198:201], v[92:95]
	v_mfma_f32_16x16x32_bf16 v[88:91], v[190:193], v[198:201], v[88:91]
	v_mfma_f32_16x16x32_bf16 v[84:87], v[182:185], v[206:209], v[84:87]
	v_mfma_f32_16x16x32_bf16 v[80:83], v[190:193], v[206:209], v[80:83]
	v_mfma_f32_16x16x32_bf16 v[76:79], v[182:185], v[220:223], v[76:79]
	v_mfma_f32_16x16x32_bf16 v[72:75], v[190:193], v[220:223], v[72:75]
	v_mfma_f32_16x16x32_bf16 v[68:71], v[182:185], v[228:231], v[68:71]
	v_mfma_f32_16x16x32_bf16 v[64:67], v[190:193], v[228:231], v[64:67]
	v_mfma_f32_16x16x32_bf16 v[92:95], v[186:189], v[202:205], v[92:95]
	v_mfma_f32_16x16x32_bf16 v[88:91], v[194:197], v[202:205], v[88:91]
	v_mfma_f32_16x16x32_bf16 v[84:87], v[186:189], v[210:213], v[84:87]
	v_mfma_f32_16x16x32_bf16 v[80:83], v[194:197], v[210:213], v[80:83]
	v_mfma_f32_16x16x32_bf16 v[76:79], v[186:189], v[224:227], v[76:79]
	v_mfma_f32_16x16x32_bf16 v[72:75], v[194:197], v[224:227], v[72:75]
	v_mfma_f32_16x16x32_bf16 v[68:71], v[186:189], v[232:235], v[68:71]
	v_mfma_f32_16x16x32_bf16 v[64:67], v[194:197], v[232:235], v[64:67]
	s_setprio 0
	s_barrier
; #define PG8_STAGE(bufoff, gbase, voff) do { _Pragma("unroll") for (int _i = 0; _i < 2; ++_i) \
;         __builtin_amdgcn_global_load_lds((const unsigned*)((const char*)(gbase) + (voff)[_i]), (PG8_LAS unsigned*)(lds + (bufoff) + ldsw + _i * 8192), 16, 0, 0); } while (0)
; #define PG8_LDA(dst, b, h) do { _Pragma("unroll") for (int m = 0; m < 4; ++m) _Pragma("unroll") for (int k = 0; k < 2; ++k) dst[m][k] = *(const PG8_LAS bf16x8*)(lds + PG8_SA(b, h) + aoff + m * 2048 + k * 1024); } while (0)
; #define PG8_MMA(ai, bj, At, Bt) do { __builtin_amdgcn_s_setprio(1); _Pragma("unroll") for (int m = 0; m < 4; ++m) _Pragma("unroll") for (int n = 0; n < 2; ++n) _Pragma("unroll") for (int k = 0; k < 2; ++k) \
;         acc[ai][bj][m][n] = __builtin_amdgcn_mfma_f32_16x16x32_bf16(Bt[n][k], At[m][k], acc[ai][bj][m][n], 0, 0, 0); __builtin_amdgcn_s_setprio(0); } while (0)
; #define PG8_WAIT_V(n) asm volatile("s_waitcnt vmcnt(" #n ")" ::: "memory")
; #define PG8_WAIT_L(n) asm volatile("s_waitcnt lgkmcnt(" #n ")" ::: "memory")
; #define PG8_BAR __builtin_amdgcn_s_barrier()
; #define PG8_SCHED __builtin_amdgcn_sched_barrier(0)
; template <class Epi, class Sched, bool ALIGN_EPI = false, bool SP2 = false>
; __device__ __forceinline__ void gemm_phase(PG8_LAS unsigned char* lds, const Gemm g, const Sched& S, const Epi& E) {
;     ...
;         for (int t = 0; t < nt; t += 2) {
;             const bool last = (t == nt - 2);
;             const char* a1 = cA + (size_t)(t + 1) * kstep;
;             const char* a2 = last ? nA : cA + (size_t)(t + 2) * kstep; const char* b2 = last ? nB : cB + (size_t)(t + 2) * kstep;
;     ...
;             PG8_LDA(At, 1, 1); PG8_STAGE(PG8_SB(1, 0), b3, voffB); PG8_STAGE(PG8_SB(1, 1), b3 + hstep, voffB); PG8_STAGE(PG8_SA(1, 0), a3, voffA);
;             PG8_WAIT_V(8); PG8_WAIT_L(0); PG8_BAR; PG8_MMA(1, 0, At, B0); PG8_MMA(1, 1, At, B1); PG8_BAR; PG8_SCHED;
	s_add_i32 s78, s75, s65
	s_add_u32 s54, s54, 0x80
	s_addc_u32 s55, s55, 0
	s_mov_b32 m0, s78
	ds_read_b128 v[198:201], v147 offset:49152
	ds_read_b128 v[202:205], v147 offset:50176
	ds_read_b128 v[206:209], v147 offset:51200
	ds_read_b128 v[210:213], v147 offset:52224
	ds_read_b128 v[220:223], v147 offset:53248
	ds_read_b128 v[224:227], v147 offset:54272
	ds_read_b128 v[228:231], v147 offset:55296
	ds_read_b128 v[232:235], v147 offset:56320
	global_load_lds_dwordx4 v130, s[54:55]
	s_add_i32 m0, s78, 0x2000
	s_add_i32 s78, s76, s65
	global_load_lds_dwordx4 v134, s[54:55]
	s_add_u32 s54, s54, 0x80000
	s_addc_u32 s55, s55, 0
	s_mov_b32 m0, s78
	s_nop 0
	global_load_lds_dwordx4 v130, s[54:55]
	s_add_i32 m0, s78, 0x2000
	s_sub_u32 s56, s56, 0x7ff80
	s_subb_u32 s57, s57, 0
	global_load_lds_dwordx4 v134, s[54:55]
	s_mov_b32 m0, s70
	s_nop 0
	global_load_lds_dwordx4 v128, s[56:57]
	s_mov_b32 m0, s71
	s_nop 0
	global_load_lds_dwordx4 v132, s[56:57]
	s_waitcnt vmcnt(8)
	s_waitcnt lgkmcnt(0)
	s_barrier
	s_setprio 1
	s_waitcnt lgkmcnt(0)
	v_mfma_f32_16x16x32_bf16 v[60:63], v[148:151], v[198:201], v[60:63]
	v_mfma_f32_16x16x32_bf16 v[56:59], v[174:177], v[198:201], v[56:59]
	v_mfma_f32_16x16x32_bf16 v[52:55], v[148:151], v[206:209], v[52:55]
	v_mfma_f32_16x16x32_bf16 v[48:51], v[174:177], v[206:209], v[48:51]
	v_mfma_f32_16x16x32_bf16 v[44:47], v[148:151], v[220:223], v[44:47]
	v_mfma_f32_16x16x32_bf16 v[40:43], v[174:177], v[220:223], v[40:43]
	v_mfma_f32_16x16x32_bf16 v[36:39], v[148:151], v[228:231], v[36:39]
	v_mfma_f32_16x16x32_bf16 v[32:35], v[174:177], v[228:231], v[32:35]
	v_mfma_f32_16x16x32_bf16 v[60:63], v[170:173], v[202:205], v[60:63]
	v_mfma_f32_16x16x32_bf16 v[56:59], v[178:181], v[202:205], v[56:59]
	v_mfma_f32_16x16x32_bf16 v[52:55], v[170:173], v[210:213], v[52:55]
	v_mfma_f32_16x16x32_bf16 v[48:51], v[178:181], v[210:213], v[48:51]
	v_mfma_f32_16x16x32_bf16 v[44:47], v[170:173], v[224:227], v[44:47]
	v_mfma_f32_16x16x32_bf16 v[40:43], v[178:181], v[224:227], v[40:43]
	v_mfma_f32_16x16x32_bf16 v[36:39], v[170:173], v[232:235], v[36:39]
	v_mfma_f32_16x16x32_bf16 v[32:35], v[178:181], v[232:235], v[32:35]
	s_setprio 0
	s_setprio 1
	v_mfma_f32_16x16x32_bf16 v[28:31], v[182:185], v[198:201], v[28:31]
	v_mfma_f32_16x16x32_bf16 v[24:27], v[190:193], v[198:201], v[24:27]
	v_mfma_f32_16x16x32_bf16 v[20:23], v[182:185], v[206:209], v[20:23]
	v_mfma_f32_16x16x32_bf16 v[16:19], v[190:193], v[206:209], v[16:19]
	v_mfma_f32_16x16x32_bf16 v[12:15], v[182:185], v[220:223], v[12:15]
	v_mfma_f32_16x16x32_bf16 v[8:11], v[190:193], v[220:223], v[8:11]
	v_mfma_f32_16x16x32_bf16 v[4:7], v[182:185], v[228:231], v[4:7]
	v_mfma_f32_16x16x32_bf16 v[0:3], v[190:193], v[228:231], v[0:3]
	v_mfma_f32_16x16x32_bf16 v[28:31], v[186:189], v[202:205], v[28:31]
	v_mfma_f32_16x16x32_bf16 v[24:27], v[194:197], v[202:205], v[24:27]
	v_mfma_f32_16x16x32_bf16 v[20:23], v[186:189], v[210:213], v[20:23]
	v_mfma_f32_16x16x32_bf16 v[16:19], v[194:197], v[210:213], v[16:19]
	v_mfma_f32_16x16x32_bf16 v[12:15], v[186:189], v[224:227], v[12:15]
	v_mfma_f32_16x16x32_bf16 v[8:11], v[194:197], v[224:227], v[8:11]
	v_mfma_f32_16x16x32_bf16 v[4:7], v[186:189], v[232:235], v[4:7]
	v_mfma_f32_16x16x32_bf16 v[0:3], v[194:197], v[232:235], v[0:3]
	s_setprio 0
	s_barrier
	s_add_i32 s74, s74, 2
	s_add_u32 s52, s52, 0x100
	s_addc_u32 s53, s53, 0
	s_cmp_gt_u32 s74, 29
	s_cbranch_scc0 .LBB0_431
	s_and_b64 vcc, exec, s[26:27]
	s_cbranch_vccz .LBB0_434
	s_barrier
